# PEER act phase fully software-pipelined: all loads of trip i+1 (ids two trips ahead, scale gathers, partial hid, gate) issued at the top of trip i into a prefetch set, trip i computes without waits
# speedup vs baseline: 1.0181x; 1.0098x over previous
.LBB0_977:
	s_or_b64 exec, exec, s[0:1]
	s_add_u32 s14, s26, 0x19000000
	v_mov_b32_e32 v33, 0
	v_readlane_b32 s0, v246, 0
	s_addc_u32 s15, s27, 0
	v_mov_b32_e32 v201, v33
	v_readlane_b32 s1, v246, 1
	s_add_u32 s12, s26, 0x1c000000
	s_addc_u32 s13, s27, 0
	v_lshl_add_u64 v[34:35], s[0:1], 0, v[200:201]
	s_mov_b64 s[0:1], 0x200000
	v_cmp_gt_u64_e32 vcc, s[0:1], v[34:35]
	s_waitcnt lgkmcnt(0)
	s_barrier
	s_and_saveexec_b64 s[10:11], vcc
	s_cbranch_execz .LBB0_996
	v_and_b32_e32 v0, 31, v200
	v_cmp_eq_u32_e64 s[40:41], 0, v0
	v_mbcnt_lo_u32_b32 v0, -1, 0
	v_mbcnt_hi_u32_b32 v0, -1, v0
	v_and_b32_e32 v2, 64, v0
	s_add_u32 s18, s26, 0.5
	v_xor_b32_e32 v1, 16, v0
	v_add_u32_e32 v2, 64, v2
	s_addc_u32 s19, s27, 0
	v_cmp_lt_i32_e32 vcc, v1, v2
	s_lshl_b64 s[0:1], s[2:3], 12
	v_lshlrev_b32_e32 v32, 3, v200
	v_readlane_b32 s30, v246, 2
	v_cndmask_b32_e32 v0, v0, v1, vcc
	v_lshl_add_u64 v[36:37], s[0:1], 0, v[32:33]
	s_lshl_b64 s[0:1], s[2:3], 13
	v_lshlrev_b32_e32 v32, 4, v200
	v_readlane_b32 s31, v246, 3
	v_lshlrev_b32_e32 v42, 2, v0
	v_lshl_add_u64 v[0:1], s[0:1], 0, v[32:33]
	s_mov_b64 s[0:1], 0x2f000000
	s_lshl_b64 s[42:43], s[30:31], 9
	v_lshl_add_u64 v[38:39], v[0:1], 0, s[0:1]
	s_lshl_b64 s[44:45], s[30:31], 13
	s_mov_b64 s[46:47], 0
	s_mov_b32 s3, 0xffff0000
	v_mov_b32_e32 v43, 0xc0135761
	s_mov_b32 s17, 0x42ee0000
	s_mov_b32 s30, 0xf000
	v_mov_b32_e32 v44, 5
	s_mov_b64 s[58:59], 0x2d000000
	s_mov_b64 s[60:61], 0x9000000
	s_mov_b64 s[62:63], 0xa000000
	s_mov_b64 s[64:65], 0xb000000
	s_mov_b64 s[66:67], 0xc000000
	v_lshl_add_u64 v[196:197], s[26:27], 0, v[36:37]
	v_lshl_add_u64 v[198:199], v[196:197], 0, s[58:59]
	global_load_dwordx2 v[140:141], v[198:199], off
	s_waitcnt vmcnt(0)
	v_lshlrev_b32_e32 v188, 5, v140
	v_lshlrev_b32_e32 v189, 5, v141
	v_and_b32_e32 v188, 0x1fffe0, v188
	v_lshlrev_b32_sdwa v190, v44, v140 dst_sel:DWORD dst_unused:UNUSED_PAD src0_sel:DWORD src1_sel:WORD_1
	v_and_b32_e32 v189, 0x1fffe0, v189
	v_lshlrev_b32_sdwa v191, v44, v141 dst_sel:DWORD dst_unused:UNUSED_PAD src0_sel:DWORD src1_sel:WORD_1
	global_load_dwordx4 v[144:147], v188, s[18:19]
	global_load_dwordx4 v[148:151], v188, s[18:19] offset:16
	global_load_dwordx4 v[152:155], v190, s[18:19]
	global_load_dwordx4 v[156:159], v190, s[18:19] offset:16
	global_load_dwordx4 v[160:163], v189, s[18:19]
	global_load_dwordx4 v[164:167], v189, s[18:19] offset:16
	global_load_dwordx4 v[168:171], v191, s[18:19]
	global_load_dwordx4 v[172:175], v191, s[18:19] offset:16
	v_lshl_add_u64 v[192:193], v[196:197], 0, s[60:61]
	global_load_dwordx2 v[128:129], v[192:193], off
	v_lshl_add_u64 v[192:193], v[196:197], 0, s[62:63]
	global_load_dwordx2 v[130:131], v[192:193], off
	v_lshl_add_u64 v[192:193], v[196:197], 0, s[64:65]
	global_load_dwordx2 v[132:133], v[192:193], off
	v_lshl_add_u64 v[192:193], v[196:197], 0, s[66:67]
	global_load_dwordx2 v[134:135], v[192:193], off
	v_lshl_add_u64 v[198:199], s[26:27], 0, v[38:39]
	global_load_dwordx4 v[136:139], v[198:199], off
	v_lshl_add_u64 v[196:197], v[196:197], 0, s[56:57]
	v_lshl_add_u64 v[196:197], v[196:197], 0, s[58:59]
	global_load_dwordx2 v[140:141], v[196:197], off
	s_waitcnt vmcnt(0)
	s_branch .LBB0_980

.LBB0_980:
	v_lshl_add_u64 v[40:41], s[26:27], 0, v[36:37]
	s_mov_b32 s0, 0xa000000
	s_waitcnt vmcnt(8)
	v_mov_b32_e32 v20, v144
	v_mov_b32_e32 v21, v145
	v_mov_b32_e32 v22, v146
	v_mov_b32_e32 v23, v147
	v_mov_b32_e32 v0, v148
	v_mov_b32_e32 v1, v149
	v_mov_b32_e32 v2, v150
	v_mov_b32_e32 v3, v151
	v_mov_b32_e32 v16, v152
	v_mov_b32_e32 v17, v153
	v_mov_b32_e32 v18, v154
	v_mov_b32_e32 v19, v155
	v_mov_b32_e32 v4, v156
	v_mov_b32_e32 v5, v157
	v_mov_b32_e32 v6, v158
	v_mov_b32_e32 v7, v159
	v_mov_b32_e32 v24, v160
	v_mov_b32_e32 v25, v161
	v_mov_b32_e32 v26, v162
	v_mov_b32_e32 v27, v163
	v_mov_b32_e32 v8, v164
	v_mov_b32_e32 v9, v165
	v_mov_b32_e32 v10, v166
	v_mov_b32_e32 v11, v167
	v_mov_b32_e32 v28, v168
	v_mov_b32_e32 v29, v169
	v_mov_b32_e32 v30, v170
	v_mov_b32_e32 v31, v171
	v_mov_b32_e32 v12, v172
	v_mov_b32_e32 v13, v173
	v_mov_b32_e32 v14, v174
	v_mov_b32_e32 v15, v175
	v_mov_b32_e32 v176, v128
	v_mov_b32_e32 v177, v129
	v_mov_b32_e32 v178, v130
	v_mov_b32_e32 v179, v131
	v_mov_b32_e32 v180, v132
	v_mov_b32_e32 v181, v133
	v_mov_b32_e32 v182, v134
	v_mov_b32_e32 v183, v135
	v_mov_b32_e32 v184, v136
	v_mov_b32_e32 v185, v137
	v_mov_b32_e32 v186, v138
	v_mov_b32_e32 v187, v139
	v_lshl_add_u64 v[196:197], v[40:41], 0, s[56:57]
	v_lshlrev_b32_e32 v188, 5, v140
	v_lshlrev_b32_e32 v189, 5, v141
	v_and_b32_e32 v188, 0x1fffe0, v188
	v_lshlrev_b32_sdwa v190, v44, v140 dst_sel:DWORD dst_unused:UNUSED_PAD src0_sel:DWORD src1_sel:WORD_1
	v_and_b32_e32 v189, 0x1fffe0, v189
	v_lshlrev_b32_sdwa v191, v44, v141 dst_sel:DWORD dst_unused:UNUSED_PAD src0_sel:DWORD src1_sel:WORD_1
	global_load_dwordx4 v[144:147], v188, s[18:19]
	global_load_dwordx4 v[148:151], v188, s[18:19] offset:16
	global_load_dwordx4 v[152:155], v190, s[18:19]
	global_load_dwordx4 v[156:159], v190, s[18:19] offset:16
	global_load_dwordx4 v[160:163], v189, s[18:19]
	global_load_dwordx4 v[164:167], v189, s[18:19] offset:16
	global_load_dwordx4 v[168:171], v191, s[18:19]
	global_load_dwordx4 v[172:175], v191, s[18:19] offset:16
	v_lshl_add_u64 v[192:193], v[196:197], 0, s[60:61]
	global_load_dwordx2 v[128:129], v[192:193], off
	v_lshl_add_u64 v[192:193], v[196:197], 0, s[62:63]
	global_load_dwordx2 v[130:131], v[192:193], off
	v_lshl_add_u64 v[192:193], v[196:197], 0, s[64:65]
	global_load_dwordx2 v[132:133], v[192:193], off
	v_lshl_add_u64 v[192:193], v[196:197], 0, s[66:67]
	global_load_dwordx2 v[134:135], v[192:193], off
	v_lshl_add_u64 v[198:199], s[26:27], 0, v[38:39]
	v_lshl_add_u64 v[198:199], v[198:199], 0, s[44:45]
	global_load_dwordx4 v[136:139], v[198:199], off
	v_lshl_add_u64 v[196:197], v[196:197], 0, s[56:57]
	v_lshl_add_u64 v[196:197], v[196:197], 0, s[58:59]
	global_load_dwordx2 v[140:141], v[196:197], off
	v_mov_b32_e32 v50, v20
	v_mov_b32_e32 v46, v176
	v_mov_b32_e32 v47, v177
	v_mov_b32_e32 v51, v16
	v_mov_b32_e32 v52, v24
	v_mov_b32_e32 v53, v28
	v_mov_b32_e32 v28, v25
	v_mov_b32_e32 v16, v21
	v_lshlrev_b32_e32 v48, 16, v46
	v_and_b32_e32 v49, 0xffff0000, v46
	v_pk_fma_f32 v[48:49], v[50:51], v[48:49], 0 op_sel_hi:[1,1,0]
	v_add_co_u32_e32 v50, vcc, s0, v40
	s_mov_b32 s0, 0xb000000
	s_nop 0
	v_addc_co_u32_e32 v51, vcc, 0, v41, vcc
	v_add_co_u32_e32 v24, vcc, s0, v40
	v_mov_b32_e32 v50, v178
	v_mov_b32_e32 v51, v179
	s_nop 0
	v_addc_co_u32_e32 v25, vcc, 0, v41, vcc
	v_mov_b32_e32 v24, v180
	v_mov_b32_e32 v25, v181
	v_lshlrev_b32_e32 v46, 16, v47
	v_and_b32_e32 v47, 0xffff0000, v47
	v_pk_fma_f32 v[46:47], v[52:53], v[46:47], 0 op_sel_hi:[1,1,0]
	s_brev_b32 s0, 48
	v_lshlrev_b32_e32 v52, 16, v50
	v_and_b32_e32 v53, 0xffff0000, v50
	v_lshlrev_b32_e32 v20, 16, v51
	v_and_b32_e32 v21, 0xffff0000, v51
	v_pk_fma_f32 v[20:21], v[28:29], v[20:21], v[46:47]
	v_pk_fma_f32 v[16:17], v[16:17], v[52:53], v[48:49]
	v_lshlrev_b32_e32 v28, 16, v24
	v_and_b32_e32 v29, 0xffff0000, v24
	v_mov_b32_e32 v46, v22
	v_mov_b32_e32 v47, v18
	v_lshlrev_b32_e32 v24, 16, v25
	v_and_b32_e32 v25, 0xffff0000, v25
	v_mov_b32_e32 v48, v26
	v_mov_b32_e32 v49, v30
	v_pk_fma_f32 v[28:29], v[46:47], v[28:29], v[16:17]
	v_pk_fma_f32 v[16:17], v[48:49], v[24:25], v[20:21]
	v_add_co_u32_e32 v20, vcc, s0, v40
	v_mov_b32_e32 v30, v27
	s_nop 0
	v_addc_co_u32_e32 v21, vcc, 0, v41, vcc
	v_mov_b32_e32 v20, v182
	v_mov_b32_e32 v21, v183
	v_mov_b32_e32 v18, v23
	v_lshlrev_b32_e32 v24, 16, v20
	v_and_b32_e32 v25, 0xffff0000, v20
	v_lshlrev_b32_e32 v20, 16, v21
	v_and_b32_e32 v21, 0xffff0000, v21
	v_pk_fma_f32 v[16:17], v[30:31], v[20:21], v[16:17]
	v_lshl_add_u64 v[20:21], s[26:27], 0, v[38:39]
	v_mov_b32_e32 v20, v184
	v_mov_b32_e32 v21, v185
	v_mov_b32_e32 v22, v186
	v_mov_b32_e32 v23, v187
	v_pk_fma_f32 v[18:19], v[18:19], v[24:25], v[28:29]
	s_nop 0
	v_mul_f32_e32 v24, v18, v18
	v_fmamk_f32 v24, v24, 0xbdd2d3e8, v43
	v_mul_f32_e32 v24, v18, v24
	v_exp_f32_e32 v24, v24
	s_nop 0
	v_add_f32_e32 v24, 1.0, v24
	v_rcp_f32_e32 v24, v24
	s_nop 0
	v_mul_f32_e32 v18, v18, v24
	v_mul_f32_e32 v20, v20, v18
	v_mul_f32_e32 v18, v19, v19
	v_fmamk_f32 v18, v18, 0xbdd2d3e8, v43
	v_mul_f32_e32 v18, v19, v18
	v_exp_f32_e32 v18, v18
	v_mul_f32_e32 v24, v0, v20
	v_add_f32_e32 v18, 1.0, v18
	v_rcp_f32_e32 v18, v18
	s_nop 0
	v_mul_f32_e32 v18, v19, v18
	v_mul_f32_e32 v21, v21, v18
	v_mul_f32_e32 v18, v16, v16
	v_fmamk_f32 v18, v18, 0xbdd2d3e8, v43
	v_mul_f32_e32 v18, v16, v18
	v_exp_f32_e32 v18, v18
	v_mul_f32_e32 v4, v4, v21
	v_max3_f32 v0, |v24|, 0, |v4|
	v_add_f32_e32 v18, 1.0, v18
	v_rcp_f32_e32 v18, v18
	s_nop 0
	v_mul_f32_e32 v16, v16, v18
	v_mul_f32_e32 v22, v22, v16
	v_mul_f32_e32 v16, v17, v17
	v_fmamk_f32 v16, v16, 0xbdd2d3e8, v43
	v_mul_f32_e32 v16, v17, v16
	v_exp_f32_e32 v16, v16
	v_mul_f32_e32 v8, v8, v22
	v_lshlrev_b32_e32 v18, 2, v34
	v_and_b32_e32 v32, 0x78, v18
	v_add_f32_e32 v16, 1.0, v16
	v_rcp_f32_e32 v16, v16
	v_lshl_add_u64 v[18:19], s[14:15], 0, v[32:33]
	v_mul_f32_e32 v16, v17, v16
	v_mul_f32_e32 v23, v23, v16
	v_mul_f32_e32 v12, v12, v23
	v_max3_f32 v0, v0, |v8|, |v12|
	v_lshrrev_b64 v[16:17], 5, v[34:35]
	s_nop 0
	v_mov_b32_dpp v25, v0 quad_perm:[1,0,3,2] row_mask:0xf bank_mask:0xf bound_ctrl:1
	v_max_f32_e32 v25, v25, v25
	v_max_f32_e32 v0, v0, v25
	s_nop 1
	v_mov_b32_dpp v25, v0 quad_perm:[2,3,0,1] row_mask:0xf bank_mask:0xf bound_ctrl:1
	v_max_f32_e32 v25, v25, v25
	v_max_f32_e32 v0, v0, v25
	s_nop 1
	v_mov_b32_dpp v25, v0 row_half_mirror row_mask:0xf bank_mask:0xf bound_ctrl:1
	v_max_f32_e32 v25, v25, v25
	v_max_f32_e32 v0, v0, v25
	s_nop 1
	v_mov_b32_dpp v25, v0 row_mirror row_mask:0xf bank_mask:0xf bound_ctrl:1
	v_max_f32_e32 v25, v25, v25
	v_max_f32_e32 v0, v0, v25
	ds_bpermute_b32 v25, v42, v0
	s_waitcnt lgkmcnt(0)
	v_max_f32_e32 v25, v25, v25
	v_max_f32_e32 v0, v0, v25
	v_div_scale_f32 v25, s[34:35], v0, v0, s17
	v_rcp_f32_e32 v26, v25
	v_cmp_lt_f32_e64 s[0:1], 0, v0
	v_fma_f32 v27, -v25, v26, 1.0
	v_fmac_f32_e32 v26, v27, v26
	v_div_scale_f32 v27, vcc, s17, v0, s17
	v_mul_f32_e32 v28, v27, v26
	v_fma_f32 v29, -v25, v28, v27
	v_fmac_f32_e32 v28, v29, v26
	v_fma_f32 v25, -v25, v28, v27
	v_div_fmas_f32 v25, v25, v26, v28
	v_div_fixup_f32 v25, v25, v0, s17
	v_cndmask_b32_e64 v25, 0, v25, s[0:1]
	v_mul_f32_e32 v24, v24, v25
	v_mul_f32_e32 v4, v4, v25
	v_mul_f32_e32 v8, v8, v25
	v_mul_f32_e32 v12, v12, v25
	v_rndne_f32_e32 v24, v24
	v_rndne_f32_e32 v4, v4
	v_rndne_f32_e32 v8, v8
	v_rndne_f32_e32 v12, v12
	v_cvt_i32_f32_e32 v24, v24
	v_cvt_i32_f32_e32 v4, v4
	v_cvt_i32_f32_e32 v8, v8
	v_cvt_i32_f32_e32 v12, v12
	v_bfe_i32 v26, v24, 0, 4
	v_bfe_i32 v27, v4, 0, 4
	v_bfe_i32 v28, v8, 0, 4
	v_bfe_i32 v25, v12, 0, 4
	v_sub_u32_e32 v26, v24, v26
	v_and_b32_e32 v24, 15, v24
	v_sub_u32_sdwa v27, v4, v27 dst_sel:WORD_1 dst_unused:UNUSED_PAD src0_sel:DWORD src1_sel:DWORD
	v_lshlrev_b32_e32 v4, 4, v4
	v_sub_u32_e32 v28, v8, v28
	v_lshlrev_b32_e32 v8, 8, v8
	v_sub_u32_sdwa v25, v12, v25 dst_sel:BYTE_3 dst_unused:UNUSED_PAD src0_sel:DWORD src1_sel:DWORD
	v_lshlrev_b32_e32 v12, 12, v12
	v_and_b32_e32 v4, 0xf0, v4
	v_and_b32_e32 v8, 0xf00, v8
	v_lshlrev_b32_e32 v28, 20, v28
	v_and_or_b32 v12, v12, s30, v24
	v_lshlrev_b32_e32 v26, 12, v26
	v_and_b32_e32 v28, 0xf000000, v28
	v_and_b32_e32 v25, 0xf0000000, v25
	v_or3_b32 v4, v12, v8, v4
	v_and_b32_e32 v26, 0xf0000, v26
	v_and_b32_e32 v27, 0xf00000, v27
	v_or3_b32 v8, v25, v28, v4
	v_or3_b32 v8, v27, v26, v8
	v_lshlrev_b64 v[24:25], 7, v[16:17]
	v_lshl_add_u64 v[18:19], v[18:19], 0, v[24:25]
	v_mov_b32_dpp v12, v8 quad_perm:[1,0,3,2] row_mask:0xf bank_mask:0xf bound_ctrl:1
	s_and_saveexec_b64 s[0:1], s[38:39]
	s_cbranch_execz .LBB0_982
	v_lshl_or_b32 v24, v12, 16, v4
	v_lshrrev_b32_e32 v4, 16, v8
	v_and_or_b32 v25, v12, s3, v4
	global_store_dwordx2 v[18:19], v[24:25], off
